# phase 6 chunk scan: three chunks in flight (loop unrolled by three, three register sets)
# baseline (speedup 1.0000x reference)
; #define LAS __attribute__((address_space(3)))
; __device__ __forceinline__ void scan_phase(const Params& p, int bid, int nblk, LAS unsigned char* lds) {
;     ...
;         auto gload = [&](int n) {
;             const size_t it = (size_t)(bh * 32 + n);
; #pragma unroll
;             for (int i = 0; i < 2; ++i) { const int ch = tid + 512 * i; r_wd[i] = *(const u32x4*)(wdc + it * 8192 + ch * 8); r_qd[i] = *(const u32x4*)(qd + it * 8192 + ch * 8); r_kt[i] = *(const u32x4*)(kt + it * 8192 + ch * 8); }
;             r_qk = *(const u32x4*)(qk + it * 4096 + tid * 8);
;             if (tid < 256) r_ub = *(const u32x4*)(ub + it * 8192 + (tid >> 2) * 128 + sl * 16 + (tid & 3) * 4);
;         };
;     ...
;         __syncthreads();
;         gload(0);
;         for (int i = tid; i < 4352 / 4; i += 512) *(LAS unsigned*)(lds + SC_ST + i * 4) = 0u;
;         lstore(0);
;         f32x4 sacc = (f32x4){0.f, 0.f, 0.f, 0.f};
;         const float cdall = cdv[bh * 32 + (lane & 31)];
;         __syncthreads();
;         for (int n = 0; n < 32; ++n) {
;             const int cur = n & 1; LAS unsigned char* B = lds + cur * SB_SIZE;
;             if (n + 1 < 32) gload(n + 1);
.Lsc_proA:
	s_or_b64 exec, exec, s[8:9]
	v_lshl_add_u64 v[140:141], s[26:27], 0, v[48:49]
	v_add_co_u32_e32 v132, vcc, 0xe541000, v140
	v_lshl_add_u64 v[148:149], s[28:29], 0, v[48:49]
	s_nop 0
	v_addc_co_u32_e32 v133, vcc, 0, v141, vcc
	v_add_co_u32_e32 v134, vcc, 0xf541000, v140
	s_nop 1
	v_addc_co_u32_e32 v135, vcc, 0, v141, vcc
	global_load_dwordx4 v[124:127], v[132:133], off
	global_load_dwordx4 v[128:131], v[134:135], off
	v_add_co_u32_e32 v132, vcc, 0x10541000, v140
	s_nop 1
	v_addc_co_u32_e32 v133, vcc, 0, v141, vcc
	v_add_co_u32_e32 v136, vcc, 0xe543000, v140
	s_nop 1
	v_addc_co_u32_e32 v137, vcc, 0, v141, vcc
	v_add_co_u32_e32 v142, vcc, 0xf543000, v140
	global_load_dwordx4 v[132:135], v[132:133], off
	s_nop 0
	global_load_dwordx4 v[136:139], v[136:137], off
	v_addc_co_u32_e32 v143, vcc, 0, v141, vcc
	v_add_co_u32_e32 v144, vcc, 0x10543000, v140
	s_nop 1
	v_addc_co_u32_e32 v145, vcc, 0, v141, vcc
	global_load_dwordx4 v[140:143], v[142:143], off
	s_nop 0
	global_load_dwordx4 v[144:147], v[144:145], off
	s_nop 0
	v_lshl_add_u64 v[148:149], v[148:149], 0, s[44:45]
	global_load_dwordx4 v[148:151], v[148:149], off
	s_and_saveexec_b64 s[8:9], s[6:7]
	s_cbranch_execz .Lsc_proB
	v_lshl_add_u64 v[152:153], v[72:73], 0, s[22:23]
	global_load_dwordx4 v[152:155], v[152:153], off
.Lsc_proB:
	s_or_b64 exec, exec, s[8:9]
	s_mov_b64 s[44:45], 0x4000
	s_mov_b64 s[48:49], 0x10000
	s_waitcnt lgkmcnt(0)
	s_barrier
	s_branch .LBB0_1080

; #define LAS __attribute__((address_space(3)))
; __device__ __forceinline__ void scan_phase(const Params& p, int bid, int nblk, LAS unsigned char* lds) {
;     ...
;         auto gload = [&](int n) {
;             const size_t it = (size_t)(bh * 32 + n);
; #pragma unroll
;             for (int i = 0; i < 2; ++i) { const int ch = tid + 512 * i; r_wd[i] = *(const u32x4*)(wdc + it * 8192 + ch * 8); r_qd[i] = *(const u32x4*)(qd + it * 8192 + ch * 8); r_kt[i] = *(const u32x4*)(kt + it * 8192 + ch * 8); }
;             r_qk = *(const u32x4*)(qk + it * 4096 + tid * 8);
;             if (tid < 256) r_ub = *(const u32x4*)(ub + it * 8192 + (tid >> 2) * 128 + sl * 16 + (tid & 3) * 4);
;         };
;     ...
;         for (int n = 0; n < 32; ++n) {
;             const int cur = n & 1; LAS unsigned char* B = lds + cur * SB_SIZE;
;             if (n + 1 < 32) gload(n + 1);
.LBB0_1080_p:
	s_cmp_lg_u32 s35, 0
	s_cbranch_scc1 .Lscan_nw_p
	s_waitcnt vmcnt(14)
.Lscan_nw_p:
	s_and_b64 vcc, exec, s[18:19]
	s_cbranch_vccnz .Lscan_skipld_p
	v_lshl_add_u64 v[24:25], s[26:27], 0, v[48:49]
	v_add_co_u32_e32 v16, vcc, 0xe545000, v24
	v_lshl_add_u64 v[32:33], s[28:29], 0, v[48:49]
	s_nop 0
	v_addc_co_u32_e32 v17, vcc, 0, v25, vcc
	v_add_co_u32_e32 v18, vcc, 0xf545000, v24
	s_nop 1
	v_addc_co_u32_e32 v19, vcc, 0, v25, vcc
	global_load_dwordx4 v[8:11], v[16:17], off
	global_load_dwordx4 v[12:15], v[18:19], off
	v_add_co_u32_e32 v16, vcc, 0x10545000, v24
	s_nop 1
	v_addc_co_u32_e32 v17, vcc, 0, v25, vcc
	v_add_co_u32_e32 v20, vcc, 0xe547000, v24
	s_nop 1
	v_addc_co_u32_e32 v21, vcc, 0, v25, vcc
	v_add_co_u32_e32 v26, vcc, 0xf547000, v24
	global_load_dwordx4 v[16:19], v[16:17], off
	s_nop 0
	global_load_dwordx4 v[20:23], v[20:21], off
	v_addc_co_u32_e32 v27, vcc, 0, v25, vcc
	v_add_co_u32_e32 v28, vcc, 0x10547000, v24
	s_nop 1
	v_addc_co_u32_e32 v29, vcc, 0, v25, vcc
	global_load_dwordx4 v[24:27], v[26:27], off
	s_nop 0
	global_load_dwordx4 v[28:31], v[28:29], off
	s_nop 0
	v_lshl_add_u64 v[32:33], v[32:33], 0, s[44:45]
	global_load_dwordx4 v[32:35], v[32:33], off
	s_and_saveexec_b64 s[8:9], s[6:7]
	s_cbranch_execz .LBB0_1082_p
	v_lshl_add_u64 v[0:1], v[72:73], 0, s[48:49]
	global_load_dwordx4 v[0:3], v[0:1], off

; #define LAS __attribute__((address_space(3)))
; __device__ __forceinline__ void scan_phase(const Params& p, int bid, int nblk, LAS unsigned char* lds) {
;     ...
;         auto gload = [&](int n) {
;             const size_t it = (size_t)(bh * 32 + n);
; #pragma unroll
;             for (int i = 0; i < 2; ++i) { const int ch = tid + 512 * i; r_wd[i] = *(const u32x4*)(wdc + it * 8192 + ch * 8); r_qd[i] = *(const u32x4*)(qd + it * 8192 + ch * 8); r_kt[i] = *(const u32x4*)(kt + it * 8192 + ch * 8); }
;             r_qk = *(const u32x4*)(qk + it * 4096 + tid * 8);
;             if (tid < 256) r_ub = *(const u32x4*)(ub + it * 8192 + (tid >> 2) * 128 + sl * 16 + (tid & 3) * 4);
;         };
;     ...
;             if (wid < 4) {
; #pragma unroll
;                 for (int j = 0; j < 4; ++j) acc[j] = *(const LAS float*)(B + SB_UB + ((tw * 16 + fq * 4 + j) * 16 + fr) * 4);
; #pragma unroll
;                 for (int kk = 0; kk < 4; ++kk) { const bf16x8 a = *(const LAS bf16x8*)(B + SB_WD + (tw * 16 + fr) * 272 + (kk * 32 + fq * 8) * 2); const bf16x8 bb = *(const LAS bf16x8*)(lds + SC_ST + fr * 272 + (kk * 32 + fq * 8) * 2);
;                     acc = __builtin_amdgcn_mfma_f32_16x16x32_bf16(a, bb, acc, 0, 0, 0); }
.Lscan_skipld_p:
	s_and_b32 s42, s35, 1
	s_mul_i32 s8, s42, 0x10400
	v_cndmask_b32_e64 v36, 0, 1, s[18:19]
	s_add_i32 s43, s8, 0
	v_readlane_b32 s16, v69, s35
	v_cmp_ne_u32_e64 s[8:9], 1, v36
	s_andn2_b64 vcc, exec, s[18:19]
	s_mov_b64 s[30:31], -1
	s_cbranch_vccnz .LBB0_1084_p
	v_add3_u32 v112, s43, v90, v84
	ds_read_b128 v[36:39], v112 offset:17408
	v_add_u32_e32 v116, v86, v84
	ds_read_b128 v[40:43], v112 offset:17472
	ds_read_b128 v[44:47], v116
	ds_read_b128 v[108:111], v116 offset:64
	s_mov_b64 s[30:31], 0
	s_waitcnt lgkmcnt(1)
	v_mfma_f32_16x16x32_bf16 v[36:39], v[36:39], v[44:47], 0
	ds_read_b128 v[44:47], v112 offset:17536
	ds_read_b128 v[112:115], v112 offset:17600
	s_waitcnt lgkmcnt(2)
	v_mfma_f32_16x16x32_bf16 v[36:39], v[40:43], v[108:111], v[36:39]
	ds_read_b128 v[40:43], v116 offset:128
	ds_read_b128 v[108:111], v116 offset:192
	s_waitcnt lgkmcnt(1)
	v_mfma_f32_16x16x32_bf16 v[36:39], v[44:47], v[40:43], v[36:39]
	s_waitcnt lgkmcnt(0)
	v_mfma_f32_16x16x32_bf16 v[36:39], v[112:115], v[108:111], v[36:39]
	v_lshl_add_u64 v[24:25], s[26:27], 0, v[48:49]
	v_add_co_u32_e32 v16, vcc, 0xe545000, v24
	v_lshl_add_u64 v[32:33], s[28:29], 0, v[48:49]
	s_nop 0
	v_addc_co_u32_e32 v17, vcc, 0, v25, vcc
	v_add_co_u32_e32 v18, vcc, 0xf545000, v24
	s_nop 1
	v_addc_co_u32_e32 v19, vcc, 0, v25, vcc
	global_load_dwordx4 v[8:11], v[16:17], off
	global_load_dwordx4 v[12:15], v[18:19], off
	v_add_co_u32_e32 v16, vcc, 0x10545000, v24
	s_nop 1
	v_addc_co_u32_e32 v17, vcc, 0, v25, vcc
	v_add_co_u32_e32 v20, vcc, 0xe547000, v24
	s_nop 1
	v_addc_co_u32_e32 v21, vcc, 0, v25, vcc
	v_add_co_u32_e32 v26, vcc, 0xf547000, v24
	global_load_dwordx4 v[16:19], v[16:17], off
	s_nop 0
	global_load_dwordx4 v[20:23], v[20:21], off
	v_addc_co_u32_e32 v27, vcc, 0, v25, vcc
	v_add_co_u32_e32 v28, vcc, 0x10547000, v24
	s_nop 1
	v_addc_co_u32_e32 v29, vcc, 0, v25, vcc
	global_load_dwordx4 v[24:27], v[26:27], off
	s_nop 0
	global_load_dwordx4 v[28:31], v[28:29], off
	s_nop 0
	v_lshl_add_u64 v[32:33], v[32:33], 0, s[44:45]
	global_load_dwordx4 v[32:35], v[32:33], off

; #define LAS __attribute__((address_space(3)))
; __device__ __forceinline__ unsigned pk2(float lo, float hi) { const f32x2 v = {lo, hi}; const bf16x2_hw b = __builtin_convertvector(v, bf16x2_hw); return __builtin_bit_cast(unsigned, b); }
; __device__ __forceinline__ void scan_phase(const Params& p, int bid, int nblk, LAS unsigned char* lds) {
;     ...
;         auto lstore = [&](int buf) {
;             LAS unsigned char* B = lds + buf * SB_SIZE;
; #pragma unroll
;             for (int i = 0; i < 2; ++i) { const int ch = tid + 512 * i; const int r = ch >> 4, c8 = (ch & 15) * 8; *(LAS u32x4*)(B + SB_WD + r * 272 + c8 * 2) = r_wd[i]; *(LAS u32x4*)(B + SB_QD + r * 272 + c8 * 2) = r_qd[i];
;                 const int d = ch >> 3, t8 = (ch & 7) * 8; *(LAS u32x4*)(B + SB_KT + d * 144 + t8 * 2) = r_kt[i]; }
;             { const int r = tid >> 3, s8 = (tid & 7) * 8; *(LAS u32x4*)(B + SB_QK + r * 144 + s8 * 2) = r_qk; }
;             if (tid < 256) *(LAS u32x4*)(B + SB_UB + (tid >> 2) * 64 + (tid & 3) * 16) = r_ub;
;         };
;     ...
;             { u32x2 w; w.x = pk2(sacc[0], sacc[1]); w.y = pk2(sacc[2], sacc[3]); *(LAS u32x2*)(lds + SC_ST + fr * 272 + (wid * 16 + fq * 4) * 2) = w; }
;             if (n + 1 < 32) lstore(cur ^ 1);
.LBB0_1088_p:
	s_xor_b32 s16, s42, 1
	s_mul_i32 s16, s16, 0x10400
	s_nop 4
	v_cvt_pk_bf16_f32 v36, v4, v5
	v_cvt_pk_bf16_f32 v37, v6, v7
	s_add_i32 s16, s16, 0
	ds_write_b64 v106, v[36:37]
	s_and_b64 vcc, exec, s[18:19]
	s_cbranch_vccnz .Lsc1_w47_p
	s_waitcnt vmcnt(16)
	s_branch .Lsc1_wd_p
.Lsc1_w47_p:
	s_waitcnt vmcnt(18)

; __device__ __forceinline__ void scan_phase(const Params& p, int bid, int nblk, LAS unsigned char* lds) {
;     ...
;         auto gload = [&](int n) {
;             const size_t it = (size_t)(bh * 32 + n);
; #pragma unroll
;             for (int i = 0; i < 2; ++i) { const int ch = tid + 512 * i; r_wd[i] = *(const u32x4*)(wdc + it * 8192 + ch * 8); r_qd[i] = *(const u32x4*)(qd + it * 8192 + ch * 8); r_kt[i] = *(const u32x4*)(kt + it * 8192 + ch * 8); }
;             r_qk = *(const u32x4*)(qk + it * 4096 + tid * 8);
;             if (tid < 256) r_ub = *(const u32x4*)(ub + it * 8192 + (tid >> 2) * 128 + sl * 16 + (tid & 3) * 4);
;         };
.Lscan_nw_q:
	s_and_b64 vcc, exec, s[18:19]
	s_cbranch_vccnz .Lscan_skipld_q
	v_lshl_add_u64 v[140:141], s[26:27], 0, v[48:49]
	v_add_co_u32_e32 v132, vcc, 0xe545000, v140
	v_lshl_add_u64 v[148:149], s[28:29], 0, v[48:49]
	s_nop 0
	v_addc_co_u32_e32 v133, vcc, 0, v141, vcc
	v_add_co_u32_e32 v134, vcc, 0xf545000, v140
	s_nop 1
	v_addc_co_u32_e32 v135, vcc, 0, v141, vcc
	global_load_dwordx4 v[124:127], v[132:133], off
	global_load_dwordx4 v[128:131], v[134:135], off
	v_add_co_u32_e32 v132, vcc, 0x10545000, v140
	s_nop 1
	v_addc_co_u32_e32 v133, vcc, 0, v141, vcc
	v_add_co_u32_e32 v136, vcc, 0xe547000, v140
	s_nop 1
	v_addc_co_u32_e32 v137, vcc, 0, v141, vcc
	v_add_co_u32_e32 v142, vcc, 0xf547000, v140
	global_load_dwordx4 v[132:135], v[132:133], off
	s_nop 0
	global_load_dwordx4 v[136:139], v[136:137], off
	v_addc_co_u32_e32 v143, vcc, 0, v141, vcc
	v_add_co_u32_e32 v144, vcc, 0x10547000, v140
	s_nop 1
	v_addc_co_u32_e32 v145, vcc, 0, v141, vcc
	global_load_dwordx4 v[140:143], v[142:143], off
	s_nop 0
	global_load_dwordx4 v[144:147], v[144:145], off
	s_nop 0
	v_lshl_add_u64 v[148:149], v[148:149], 0, s[44:45]
	global_load_dwordx4 v[148:151], v[148:149], off
	s_and_saveexec_b64 s[8:9], s[6:7]
	s_cbranch_execz .LBB0_1082_q
	v_lshl_add_u64 v[152:153], v[72:73], 0, s[48:49]
	global_load_dwordx4 v[152:155], v[152:153], off

; #define LAS __attribute__((address_space(3)))
; __device__ __forceinline__ void scan_phase(const Params& p, int bid, int nblk, LAS unsigned char* lds) {
;     ...
;         auto gload = [&](int n) {
;             const size_t it = (size_t)(bh * 32 + n);
; #pragma unroll
;             for (int i = 0; i < 2; ++i) { const int ch = tid + 512 * i; r_wd[i] = *(const u32x4*)(wdc + it * 8192 + ch * 8); r_qd[i] = *(const u32x4*)(qd + it * 8192 + ch * 8); r_kt[i] = *(const u32x4*)(kt + it * 8192 + ch * 8); }
;             r_qk = *(const u32x4*)(qk + it * 4096 + tid * 8);
;             if (tid < 256) r_ub = *(const u32x4*)(ub + it * 8192 + (tid >> 2) * 128 + sl * 16 + (tid & 3) * 4);
;         };
;     ...
;             if (wid < 4) {
; #pragma unroll
;                 for (int j = 0; j < 4; ++j) acc[j] = *(const LAS float*)(B + SB_UB + ((tw * 16 + fq * 4 + j) * 16 + fr) * 4);
; #pragma unroll
;                 for (int kk = 0; kk < 4; ++kk) { const bf16x8 a = *(const LAS bf16x8*)(B + SB_WD + (tw * 16 + fr) * 272 + (kk * 32 + fq * 8) * 2); const bf16x8 bb = *(const LAS bf16x8*)(lds + SC_ST + fr * 272 + (kk * 32 + fq * 8) * 2);
;                     acc = __builtin_amdgcn_mfma_f32_16x16x32_bf16(a, bb, acc, 0, 0, 0); }
.Lscan_skipld_q:
	s_and_b32 s42, s35, 1
	s_mul_i32 s8, s42, 0x10400
	v_cndmask_b32_e64 v36, 0, 1, s[18:19]
	s_add_i32 s43, s8, 0
	v_readlane_b32 s16, v69, s35
	v_cmp_ne_u32_e64 s[8:9], 1, v36
	s_andn2_b64 vcc, exec, s[18:19]
	s_mov_b64 s[30:31], -1
	s_cbranch_vccnz .LBB0_1084_q
	v_add3_u32 v112, s43, v90, v84
	ds_read_b128 v[36:39], v112 offset:17408
	v_add_u32_e32 v116, v86, v84
	ds_read_b128 v[40:43], v112 offset:17472
	ds_read_b128 v[44:47], v116
	ds_read_b128 v[108:111], v116 offset:64
	s_mov_b64 s[30:31], 0
	s_waitcnt lgkmcnt(1)
	v_mfma_f32_16x16x32_bf16 v[36:39], v[36:39], v[44:47], 0
	ds_read_b128 v[44:47], v112 offset:17536
	ds_read_b128 v[112:115], v112 offset:17600
	s_waitcnt lgkmcnt(2)
	v_mfma_f32_16x16x32_bf16 v[36:39], v[40:43], v[108:111], v[36:39]
	ds_read_b128 v[40:43], v116 offset:128
	ds_read_b128 v[108:111], v116 offset:192
	s_waitcnt lgkmcnt(1)
	v_mfma_f32_16x16x32_bf16 v[36:39], v[44:47], v[40:43], v[36:39]
	s_waitcnt lgkmcnt(0)
	v_mfma_f32_16x16x32_bf16 v[36:39], v[112:115], v[108:111], v[36:39]
	v_lshl_add_u64 v[140:141], s[26:27], 0, v[48:49]
	v_add_co_u32_e32 v132, vcc, 0xe545000, v140
	v_lshl_add_u64 v[148:149], s[28:29], 0, v[48:49]
	s_nop 0
	v_addc_co_u32_e32 v133, vcc, 0, v141, vcc
	v_add_co_u32_e32 v134, vcc, 0xf545000, v140
	s_nop 1
	v_addc_co_u32_e32 v135, vcc, 0, v141, vcc
	global_load_dwordx4 v[124:127], v[132:133], off
	global_load_dwordx4 v[128:131], v[134:135], off
	v_add_co_u32_e32 v132, vcc, 0x10545000, v140
	s_nop 1
	v_addc_co_u32_e32 v133, vcc, 0, v141, vcc
	v_add_co_u32_e32 v136, vcc, 0xe547000, v140
	s_nop 1
	v_addc_co_u32_e32 v137, vcc, 0, v141, vcc
	v_add_co_u32_e32 v142, vcc, 0xf547000, v140
	global_load_dwordx4 v[132:135], v[132:133], off
	s_nop 0
	global_load_dwordx4 v[136:139], v[136:137], off
	v_addc_co_u32_e32 v143, vcc, 0, v141, vcc
	v_add_co_u32_e32 v144, vcc, 0x10547000, v140
	s_nop 1
	v_addc_co_u32_e32 v145, vcc, 0, v141, vcc
	global_load_dwordx4 v[140:143], v[142:143], off
	s_nop 0
	global_load_dwordx4 v[144:147], v[144:145], off
	s_nop 0
	v_lshl_add_u64 v[148:149], v[148:149], 0, s[44:45]
	global_load_dwordx4 v[148:151], v[148:149], off

; #define LAS __attribute__((address_space(3)))
; __device__ __forceinline__ void scan_phase(const Params& p, int bid, int nblk, LAS unsigned char* lds) {
;     ...
;         auto lstore = [&](int buf) {
;             LAS unsigned char* B = lds + buf * SB_SIZE;
; #pragma unroll
;             for (int i = 0; i < 2; ++i) { const int ch = tid + 512 * i; const int r = ch >> 4, c8 = (ch & 15) * 8; *(LAS u32x4*)(B + SB_WD + r * 272 + c8 * 2) = r_wd[i]; *(LAS u32x4*)(B + SB_QD + r * 272 + c8 * 2) = r_qd[i];
;                 const int d = ch >> 3, t8 = (ch & 7) * 8; *(LAS u32x4*)(B + SB_KT + d * 144 + t8 * 2) = r_kt[i]; }
;             { const int r = tid >> 3, s8 = (tid & 7) * 8; *(LAS u32x4*)(B + SB_QK + r * 144 + s8 * 2) = r_qk; }
;             if (tid < 256) *(LAS u32x4*)(B + SB_UB + (tid >> 2) * 64 + (tid & 3) * 16) = r_ub;
;         };
.Lsc2_wd_q:
	v_add3_u32 v36, s16, v77, v76
	ds_write_b128 v36, v[186:189]
	ds_write_b128 v36, v[190:193] offset:17408
	v_add3_u32 v186, s16, v79, v78
	v_add3_u32 v187, s16, v80, v76
	ds_write_b128 v186, v[194:197] offset:34816
	ds_write_b128 v187, v[198:201]
	ds_write_b128 v187, v[202:205] offset:17408
	v_add3_u32 v187, s16, v81, v78
	ds_write_b128 v187, v[206:209] offset:34816
	ds_write_b128 v186, v[210:213] offset:53248
	s_and_saveexec_b64 s[30:31], s[6:7]
	s_cbranch_execz .LBB0_1079_q
	v_add3_u32 v186, s16, v82, v83
	ds_write_b128 v186, v[214:217] offset:62464
	s_branch .LBB0_1079_q

; __device__ __forceinline__ void scan_phase(const Params& p, int bid, int nblk, LAS unsigned char* lds) {
;     ...
;         auto gload = [&](int n) {
;             const size_t it = (size_t)(bh * 32 + n);
; #pragma unroll
;             for (int i = 0; i < 2; ++i) { const int ch = tid + 512 * i; r_wd[i] = *(const u32x4*)(wdc + it * 8192 + ch * 8); r_qd[i] = *(const u32x4*)(qd + it * 8192 + ch * 8); r_kt[i] = *(const u32x4*)(kt + it * 8192 + ch * 8); }
;             r_qk = *(const u32x4*)(qk + it * 4096 + tid * 8);
;             if (tid < 256) r_ub = *(const u32x4*)(ub + it * 8192 + (tid >> 2) * 128 + sl * 16 + (tid & 3) * 4);
;         };
.Lscan_nw:
	s_and_b64 vcc, exec, s[18:19]
	s_cbranch_vccnz .Lscan_skipld
	v_lshl_add_u64 v[202:203], s[26:27], 0, v[48:49]
	v_add_co_u32_e32 v194, vcc, 0xe545000, v202
	v_lshl_add_u64 v[210:211], s[28:29], 0, v[48:49]
	s_nop 0
	v_addc_co_u32_e32 v195, vcc, 0, v203, vcc
	v_add_co_u32_e32 v196, vcc, 0xf545000, v202
	s_nop 1
	v_addc_co_u32_e32 v197, vcc, 0, v203, vcc
	global_load_dwordx4 v[186:189], v[194:195], off
	global_load_dwordx4 v[190:193], v[196:197], off
	v_add_co_u32_e32 v194, vcc, 0x10545000, v202
	s_nop 1
	v_addc_co_u32_e32 v195, vcc, 0, v203, vcc
	v_add_co_u32_e32 v198, vcc, 0xe547000, v202
	s_nop 1
	v_addc_co_u32_e32 v199, vcc, 0, v203, vcc
	v_add_co_u32_e32 v204, vcc, 0xf547000, v202
	global_load_dwordx4 v[194:197], v[194:195], off
	s_nop 0
	global_load_dwordx4 v[198:201], v[198:199], off
	v_addc_co_u32_e32 v205, vcc, 0, v203, vcc
	v_add_co_u32_e32 v206, vcc, 0x10547000, v202
	s_nop 1
	v_addc_co_u32_e32 v207, vcc, 0, v203, vcc
	global_load_dwordx4 v[202:205], v[204:205], off
	s_nop 0
	global_load_dwordx4 v[206:209], v[206:207], off
	s_nop 0
	v_lshl_add_u64 v[210:211], v[210:211], 0, s[44:45]
	global_load_dwordx4 v[210:213], v[210:211], off
	s_and_saveexec_b64 s[8:9], s[6:7]
	s_cbranch_execz .LBB0_1082
	v_lshl_add_u64 v[214:215], v[72:73], 0, s[48:49]
	global_load_dwordx4 v[214:217], v[214:215], off

; #define LAS __attribute__((address_space(3)))
; __device__ __forceinline__ void scan_phase(const Params& p, int bid, int nblk, LAS unsigned char* lds) {
;     ...
;         auto gload = [&](int n) {
;             const size_t it = (size_t)(bh * 32 + n);
; #pragma unroll
;             for (int i = 0; i < 2; ++i) { const int ch = tid + 512 * i; r_wd[i] = *(const u32x4*)(wdc + it * 8192 + ch * 8); r_qd[i] = *(const u32x4*)(qd + it * 8192 + ch * 8); r_kt[i] = *(const u32x4*)(kt + it * 8192 + ch * 8); }
;             r_qk = *(const u32x4*)(qk + it * 4096 + tid * 8);
;             if (tid < 256) r_ub = *(const u32x4*)(ub + it * 8192 + (tid >> 2) * 128 + sl * 16 + (tid & 3) * 4);
;         };
;     ...
;             if (wid < 4) {
; #pragma unroll
;                 for (int j = 0; j < 4; ++j) acc[j] = *(const LAS float*)(B + SB_UB + ((tw * 16 + fq * 4 + j) * 16 + fr) * 4);
; #pragma unroll
;                 for (int kk = 0; kk < 4; ++kk) { const bf16x8 a = *(const LAS bf16x8*)(B + SB_WD + (tw * 16 + fr) * 272 + (kk * 32 + fq * 8) * 2); const bf16x8 bb = *(const LAS bf16x8*)(lds + SC_ST + fr * 272 + (kk * 32 + fq * 8) * 2);
;                     acc = __builtin_amdgcn_mfma_f32_16x16x32_bf16(a, bb, acc, 0, 0, 0); }
.Lscan_skipld:
	s_and_b32 s42, s35, 1
	s_mul_i32 s8, s42, 0x10400
	v_cndmask_b32_e64 v36, 0, 1, s[18:19]
	s_add_i32 s43, s8, 0
	v_readlane_b32 s16, v69, s35
	v_cmp_ne_u32_e64 s[8:9], 1, v36
	s_andn2_b64 vcc, exec, s[18:19]
	s_mov_b64 s[30:31], -1
	s_cbranch_vccnz .LBB0_1084
	v_add3_u32 v112, s43, v90, v84
	ds_read_b128 v[36:39], v112 offset:17408
	v_add_u32_e32 v116, v86, v84
	ds_read_b128 v[40:43], v112 offset:17472
	ds_read_b128 v[44:47], v116
	ds_read_b128 v[108:111], v116 offset:64
	s_mov_b64 s[30:31], 0
	s_waitcnt lgkmcnt(1)
	v_mfma_f32_16x16x32_bf16 v[36:39], v[36:39], v[44:47], 0
	ds_read_b128 v[44:47], v112 offset:17536
	ds_read_b128 v[112:115], v112 offset:17600
	s_waitcnt lgkmcnt(2)
	v_mfma_f32_16x16x32_bf16 v[36:39], v[40:43], v[108:111], v[36:39]
	ds_read_b128 v[40:43], v116 offset:128
	ds_read_b128 v[108:111], v116 offset:192
	s_waitcnt lgkmcnt(1)
	v_mfma_f32_16x16x32_bf16 v[36:39], v[44:47], v[40:43], v[36:39]
	s_waitcnt lgkmcnt(0)
	v_mfma_f32_16x16x32_bf16 v[36:39], v[112:115], v[108:111], v[36:39]
	v_lshl_add_u64 v[202:203], s[26:27], 0, v[48:49]
	v_add_co_u32_e32 v194, vcc, 0xe545000, v202
	v_lshl_add_u64 v[210:211], s[28:29], 0, v[48:49]
	s_nop 0
	v_addc_co_u32_e32 v195, vcc, 0, v203, vcc
	v_add_co_u32_e32 v196, vcc, 0xf545000, v202
	s_nop 1
	v_addc_co_u32_e32 v197, vcc, 0, v203, vcc
	global_load_dwordx4 v[186:189], v[194:195], off
	global_load_dwordx4 v[190:193], v[196:197], off
	v_add_co_u32_e32 v194, vcc, 0x10545000, v202
	s_nop 1
	v_addc_co_u32_e32 v195, vcc, 0, v203, vcc
	v_add_co_u32_e32 v198, vcc, 0xe547000, v202
	s_nop 1
	v_addc_co_u32_e32 v199, vcc, 0, v203, vcc
	v_add_co_u32_e32 v204, vcc, 0xf547000, v202
	global_load_dwordx4 v[194:197], v[194:195], off
	s_nop 0
	global_load_dwordx4 v[198:201], v[198:199], off
	v_addc_co_u32_e32 v205, vcc, 0, v203, vcc
	v_add_co_u32_e32 v206, vcc, 0x10547000, v202
	s_nop 1
	v_addc_co_u32_e32 v207, vcc, 0, v203, vcc
	global_load_dwordx4 v[202:205], v[204:205], off
	s_nop 0
	global_load_dwordx4 v[206:209], v[206:207], off
	s_nop 0
	v_lshl_add_u64 v[210:211], v[210:211], 0, s[44:45]
	global_load_dwordx4 v[210:213], v[210:211], off
